# weight conversion: two adjacent 64-column tiles per iteration (512 B contiguous per source row, shared kscale), first tile through the pipelined loop
# speedup vs baseline: 1.0057x; 1.0057x over previous
; #define LAS __attribute__((address_space(3)))
; __device__ __forceinline__ KP kp_fresh(KP k) { asm volatile("" : "+s"(k)); return k; }
; __device__ __forceinline__ int tid_fresh(int wid) { return wid * 64 + lane_id(); }
; __device__ __forceinline__ void prologue_weights(KP kp, LAS float* tile, int wid0) {
;     kp = kp_fresh(kp);
;     const int tid = tid_fresh(wid0);
;     int ti = blockIdx.x;
;     if (ti >= W_TILES) return;
;     WTile w = wtile_decode(kp, ti);
;     float v[8];
;     wtile_load(w, tid, v);
;     int par = 0;
;     for (;;) {
.LBB0_5:
	s_or_b64 exec, exec, s[2:3]
	s_mov_b64 s[8:9], s[88:89]
	s_cmpk_gt_i32 s33, 0x271f
	v_mbcnt_lo_u32_b32 v14, -1, 0
	v_mbcnt_hi_u32_b32 v14, -1, v14
	s_cbranch_scc1 .LBB0_161
	s_load_dwordx2 s[14:15], s[8:9], 0x98
	v_and_b32_e32 v20, 63, v14
	v_add_u32_e32 v15, s61, v14
	v_ashrrev_i32_e32 v21, 6, v15
	s_waitcnt lgkmcnt(0)
	s_add_u32 s28, s14, 0x5140000
	s_addc_u32 s29, s15, 0
	s_add_u32 s30, s14, 0x4d40000
	s_addc_u32 s31, s15, 0
	s_add_u32 s34, s14, 0x4b40000
	s_addc_u32 s35, s15, 0
	s_add_u32 s36, s14, 0x4900000
	s_addc_u32 s37, s15, 0
	s_add_u32 s40, s14, 0x4600000
	s_addc_u32 s41, s15, 0
	s_add_u32 s42, s14, 0x3000000
	v_lshlrev_b32_e32 v10, 3, v14
	s_addc_u32 s43, s15, 0
	v_and_b32_e32 v10, 56, v10
	s_add_u32 s44, s14, 0x400000
	s_movk_i32 s2, 0x104
	v_ashrrev_i32_e32 v13, 3, v15
	v_mov_b32_e32 v11, 0
	s_addc_u32 s45, s15, 0
	v_and_or_b32 v12, v14, 31, 64
	v_mul_lo_u32 v22, v21, s2
	v_mul_u32_u24_e32 v23, 0x104, v10
	s_mov_b32 s15, 0
	v_lshlrev_b32_e32 v24, 2, v20
	s_movk_i32 s46, 0x3ff
	s_movk_i32 s47, 0x60
	v_lshlrev_b32_e32 v14, 1, v10
	s_mov_b32 s48, 0
	s_mov_b32 s49, s33
	v_mov_b32_e32 v40, 1.0
	v_mov_b32_e32 v41, 1.0
	v_mov_b32_e32 v42, 1.0
	v_mov_b32_e32 v43, 1.0
	v_mov_b32_e32 v44, 1.0
	v_mov_b32_e32 v45, 1.0
	v_mov_b32_e32 v46, 1.0
	v_mov_b32_e32 v47, 1.0
	v_mov_b32_e32 v48, 1.0
	s_lshl_b32 s56, s33, 1
	s_mov_b64 s[16:17], 0
	s_mov_b64 s[18:19], -1
	s_mov_b32 s57, 1
	s_branch .Lpw_decode

; #define LAS __attribute__((address_space(3)))
; __device__ __forceinline__ WTile wtile_decode(KP kp, int ti) {
;     constexpr int T_UP = 1408, T_DOWN = 704, T_DQKV = 192, T_UQ = 144, T_UKV = 128, T_O = 256, T_PG = 16;
;     constexpr int B1 = 4 * T_UP, B2 = B1 + 4 * T_DOWN, B3 = B2 + 2 * T_DQKV, B4 = B3 + 2 * T_UQ, B5 = B4 + 2 * T_UKV, B6 = B5 + 2 * T_O;
;     unsigned char* ws = kp->ws; WTile w; w.scale = nullptr; w.kscale = nullptr; w.map = 0; int nkt, loc;
;     if (ti < B1)      { const int l = ti / T_UP; loc = ti % T_UP; w.src = kp->in[14] + (size_t)l * 1024 * 5632; w.dst = (bf16*)(ws + W_UP + l * SZ_UP); w.K = 1024; w.Nsrc = 5632; nkt = 16; w.map = 2; w.kscale = kp->in[4] + l * 1024; }
;     else if (ti < B2) { const int q = ti - B1, l = q / T_DOWN; loc = q % T_DOWN; w.src = kp->in[17] + (size_t)l * 2816 * 1024; w.dst = (bf16*)(ws + W_DOWN + l * SZ_DOWN); w.K = 2816; w.Nsrc = 1024; nkt = 44; }
;     else if (ti < B3) { const int q = ti - B2, l = q / T_DQKV; loc = q % T_DQKV; w.src = kp->in[6] + (size_t)l * 1024 * 672; w.dst = (bf16*)(ws + W_DQKV + l * SZ_DQKV); w.K = 1024; w.Nsrc = 672; nkt = 16; w.kscale = kp->in[2] + (2 * l) * 1024; }
;     else if (ti < B4) { const int q = ti - B3, l = q / T_UQ; loc = q % T_UQ; w.src = kp->in[8] + (size_t)l * 384 * 1536; w.dst = (bf16*)(ws + W_UQ + l * SZ_UQ); w.K = 384; w.Nsrc = 1536; nkt = 6; w.map = 1; w.kscale = kp->in[7] + l * 384; }
;     else if (ti < B5) { const int q = ti - B4, l = q / T_UKV; loc = q % T_UKV; w.src = kp->in[10] + (size_t)l * 256 * 2048; w.dst = (bf16*)(ws + W_UKV + l * SZ_UKV); w.K = 256; w.Nsrc = 2048; nkt = 4; w.kscale = kp->in[9] + l * 256; }
;     else if (ti < B6) { const int q = ti - B5, l = q / T_O; loc = q % T_O; w.src = kp->in[11] + (size_t)l * 1024 * 1024; w.dst = (bf16*)(ws + W_O + l * SZ_O); w.K = 1024; w.Nsrc = 1024; nkt = 16; }
; __device__ __forceinline__ void prologue_weights(KP kp, LAS float* tile, int wid0) {
;     ...
;     for (;;) {
;         LAS float* tb = tile + par * (64 * 65);
; #pragma unroll
;         for (int i = 0; i < 8; ++i) tb[(i * 8 + (tid >> 6)) * 65 + (tid & 63)] = v[i];
;         __syncthreads();
;         const int tn = ti + (int)gridDim.x; const bool more = tn < W_TILES;
;         WTile wn = w;
;         if (more) { wn = wtile_decode(kp, tn); wtile_load(wn, tid, v); }
.LBB0_83:
	s_mul_i32 s2, s48, 0x8200
	s_add_i32 s13, s2, 0
	s_lshl_b32 s2, s38, 1
	s_add_i32 s56, s49, s2
	s_cmpk_lt_i32 s56, 0x2720
	s_cselect_b64 s[18:19], -1, 0
	s_cmpk_gt_i32 s56, 0x271f
	s_cselect_b64 s[16:17], -1, 0
	s_waitcnt vmcnt(0)
	v_mul_f32_e32 v2, v40, v2
	v_mul_f32_e32 v9, v40, v9
	v_mul_f32_e32 v4, v40, v4
	v_mul_f32_e32 v3, v40, v3
	v_mul_f32_e32 v6, v40, v6
	v_mul_f32_e32 v5, v40, v5
	v_mul_f32_e32 v8, v40, v8
	v_mul_f32_e32 v7, v40, v7
	v_mul_f32_e32 v50, v60, v50
	v_mul_f32_e32 v51, v60, v51
	v_mul_f32_e32 v52, v60, v52
	v_mul_f32_e32 v53, v60, v53
	v_mul_f32_e32 v54, v60, v54
	v_mul_f32_e32 v55, v60, v55
	v_mul_f32_e32 v56, v60, v56
	v_mul_f32_e32 v57, v60, v57
	v_mul_f32_e32 v2, v2, v41
	v_mul_f32_e32 v9, v9, v42
	v_mul_f32_e32 v4, v4, v43
	v_mul_f32_e32 v3, v3, v44
	v_mul_f32_e32 v6, v6, v45
	v_mul_f32_e32 v5, v5, v46
	v_mul_f32_e32 v8, v8, v47
	v_mul_f32_e32 v7, v7, v48
	v_mul_f32_e32 v50, v50, v41
	v_mul_f32_e32 v51, v51, v42
	v_mul_f32_e32 v52, v52, v43
	v_mul_f32_e32 v53, v53, v44
	v_mul_f32_e32 v54, v54, v45
	v_mul_f32_e32 v55, v55, v46
	v_mul_f32_e32 v56, v56, v47
	v_mul_f32_e32 v57, v57, v48
	v_add3_u32 v10, s13, v24, v22
	s_and_b64 vcc, exec, s[16:17]
	s_mov_b64 s[20:21], s[10:11]
	s_mov_b32 s14, s0
	s_mov_b32 s53, s12
	s_mov_b32 s52, s1
	ds_write_b32 v10, v2
	ds_write_b32 v10, v9 offset:2080
	ds_write_b32 v10, v4 offset:4160
	ds_write_b32 v10, v3 offset:6240
	ds_write_b32 v10, v6 offset:8320
	ds_write_b32 v10, v5 offset:10400
	ds_write_b32 v10, v8 offset:12480
	ds_write_b32 v10, v7 offset:14560
	ds_write_b32 v10, v50 offset:16640
	ds_write_b32 v10, v51 offset:18720
	ds_write_b32 v10, v52 offset:20800
	ds_write_b32 v10, v53 offset:22880
	ds_write_b32 v10, v54 offset:24960
	ds_write_b32 v10, v55 offset:27040
	ds_write_b32 v10, v56 offset:29120
	ds_write_b32 v10, v57 offset:31200
	s_waitcnt lgkmcnt(0)
	s_barrier
	s_cbranch_vccnz .LBB0_157
.Lpw_decode:
	s_mov_b32 s50, s56
	s_cmpk_gt_i32 s50, 0x15ff
	s_cselect_b64 s[4:5], -1, 0
	s_mov_b64 s[26:27], -1
	s_and_b64 vcc, exec, s[4:5]
	s_cbranch_vccz .LBB0_106
	s_cmpk_gt_u32 s50, 0x20ff
	s_cbranch_scc0 .LBB0_102
	s_cmpk_gt_u32 s50, 0x227f
	s_cbranch_scc0 .LBB0_99
	s_cmpk_gt_u32 s50, 0x239f
	s_cbranch_scc0 .LBB0_96
	s_cmpk_gt_u32 s50, 0x249f
	s_cbranch_scc0 .LBB0_93
	s_cmpk_gt_u32 s50, 0x269f
	s_cbranch_scc0 .LBB0_91
	s_load_dwordx4 s[20:23], s[8:9], 0x60
	s_load_dwordx2 s[26:27], s[8:9], 0x10
	s_add_i32 s51, s50, 0xffffd960
	s_lshr_b32 s14, s51, 4
	s_and_b32 s52, s50, 15
	s_lshl_b64 s[2:3], s[14:15], 18
	s_waitcnt lgkmcnt(0)
	s_add_u32 s2, s20, s2
	s_addc_u32 s3, s21, s3
	s_lshl_b64 s[20:21], s[14:15], 17
	s_add_u32 s20, s28, s20
	s_addc_u32 s21, s29, s21
	s_lshl_b32 s14, s14, 8
	s_lshl_b64 s[24:25], s[14:15], 2
	s_add_u32 s24, s22, s24
	s_addc_u32 s25, s23, s25
	s_lshl_b32 s14, s51, 5
	s_and_b32 s14, s14, 0x7ffff800
	s_lshl_b64 s[22:23], s[14:15], 2
	s_add_u32 s14, s26, s22
	s_addc_u32 s22, s27, s23
	s_lshl_b32 s23, s51, 6
	s_and_b32 s23, s23, 0xc00
	s_add_u32 s14, s14, s23
	s_addc_u32 s23, s22, 0
	s_add_u32 s22, s14, 0x1000
	s_addc_u32 s23, s23, 0
	s_mov_b64 s[26:27], 0

; __device__ __forceinline__ WTile wtile_decode(KP kp, int ti) {
;     ...
;     { const int ntiles_n = (ti < B1 ? T_UP : ti < B2 ? T_DOWN : ti < B3 ? T_DQKV : ti < B4 ? T_UQ : ti < B5 ? T_UKV : ti < B6 ? T_O : T_PG) / nkt;
;       w.n0 = (loc % ntiles_n) * 64; w.k0 = (loc / ntiles_n) * 64; }
.LBB0_110:
	s_mov_b32 s60, s54
	s_and_b32 s5, 0xffff, s53
	v_cvt_f32_u32_e32 v2, s5
	s_and_b32 s4, 0xffff, s4
	v_cvt_f32_u32_e32 v3, s4
	v_rcp_iflag_f32_e32 v4, v2
	s_nop 0
	v_mul_f32_e32 v4, v3, v4
	v_trunc_f32_e32 v4, v4
	v_cvt_u32_f32_e32 v5, v4
	v_fma_f32 v3, -v4, v2, v3
	v_cmp_ge_f32_e64 s[4:5], |v3|, v2
	s_cmp_lg_u64 s[4:5], 0
	v_readfirstlane_b32 s4, v5
	s_addc_u32 s26, s4, 0
	s_sext_i32_i16 s4, s26
	v_cvt_f32_i32_e32 v2, s4
	s_sext_i32_i16 s5, s52
	v_cvt_f32_i32_e32 v3, s5
	s_xor_b32 s4, s5, s4
	v_rcp_iflag_f32_e32 v4, v2
	s_ashr_i32 s4, s4, 30
	s_or_b32 s27, s4, 1
	v_mul_f32_e32 v4, v3, v4
	v_trunc_f32_e32 v4, v4
	v_fma_f32 v3, -v4, v2, v3
	v_cvt_i32_f32_e32 v4, v4
	v_cmp_ge_f32_e64 s[4:5], |v3|, |v2|
	s_and_b64 s[4:5], s[4:5], exec
	s_cselect_b32 s4, s27, 0
	v_readfirstlane_b32 s53, v4
	s_add_i32 s53, s53, s4
	s_mul_i32 s4, s53, s26
	s_sub_i32 s4, s52, s4
	s_sext_i32_i16 s26, s4
	s_lshl_b32 s52, s26, 6
	v_or_b32_e32 v2, s52, v20
	s_cmp_gt_i32 s54, 1
	s_mov_b64 s[4:5], -1
	s_cbranch_scc0 .LBB0_112
	s_bfe_i32 s4, s26, 0x10001
	s_lshl_b32 s5, s26, 5
	s_and_b32 s4, s4, 0xb00
	s_and_b32 s5, s5, 0xffffff80
	s_add_i32 s4, s4, s5
	v_and_b32_e32 v3, 0x7f, v2
	v_or_b32_e32 v10, s4, v3
	s_mov_b64 s[4:5], 0

; __device__ __forceinline__ void wtile_load(const WTile& w, int tid, float (&v)[8]) {
;     const int n = w.n0 + (tid & 63);
;     int sc;
;     if (w.map == 1) sc = n < 1024 ? (n >> 6) * 96 + (n & 63) : ((n - 1024) >> 5) * 96 + 64 + ((n - 1024) & 31);
;     else if (w.map == 2) sc = ((n >> 7) & 1) * 2816 + (n >> 8) * 128 + (n & 127);
;     else sc = n < w.Nsrc ? n : -1;
;     const float s = w.scale ? w.scale[n] : 1.0f;
.LBB0_121:
	v_add_u32_e32 v58, 64, v2
	v_cmp_gt_i32_e32 vcc, s51, v58
	s_cmp_lg_u32 s60, 0
	s_cselect_b64 s[58:59], -1, 0
	s_or_b64 s[58:59], s[58:59], vcc
	s_cmpk_lt_u32 s52, 0x400
	s_movk_i32 s5, 0x300
	s_cselect_b32 s5, 0x180, s5
	s_cmp_eq_u32 s60, 1
	s_cselect_b32 s60, s5, 0x100
	v_mov_b32_e32 v60, 1.0
	s_cmp_eq_u64 s[24:25], 0
	s_cbranch_scc1 .LBB0_123
	v_ashrrev_i32_e32 v3, 31, v2
	v_lshl_add_u64 v[2:3], v[2:3], 2, s[24:25]
	global_load_dword v40, v[2:3], off
	s_mov_b64 s[4:5], exec
	s_and_b64 exec, exec, s[58:59]
	global_load_dword v60, v[2:3], off offset:256
	s_mov_b64 exec, s[4:5]
	s_branch .LBB0_124

; __device__ __forceinline__ void wtile_load(const WTile& w, int tid, float (&v)[8]) {
;     ...
; #pragma unroll
;     for (int i = 0; i < 8; ++i) { const int k = i * 8 + (tid >> 6); v[i] = sc >= 0 ? __builtin_nontemporal_load(w.src + (size_t)(w.k0 + k) * w.Nsrc + sc) * s * (w.kscale ? w.kscale[w.k0 + k] : 1.0f) : 0.f; }
.LBB0_124:
	s_sext_i32_i16 s53, s53
	s_lshl_b32 s53, s53, 6
	v_add_u32_e32 v16, s53, v21
	v_lshl_add_u64 v[18:19], v[10:11], 2, s[2:3]
	v_mul_lo_u32 v26, v16, s51
	v_mov_b32_e32 v27, 0
	v_ashrrev_i32_e32 v17, 31, v16
	s_lshl_b32 s4, s51, 3
	v_mov_b32_e32 v2, 0
	v_mov_b32_e32 v9, 0
	v_mov_b32_e32 v4, 0
	v_mov_b32_e32 v3, 0
	v_mov_b32_e32 v6, 0
	v_mov_b32_e32 v5, 0
	v_mov_b32_e32 v8, 0
	v_mov_b32_e32 v7, 0
	v_mov_b32_e32 v50, 0
	v_mov_b32_e32 v51, 0
	v_mov_b32_e32 v52, 0
	v_mov_b32_e32 v53, 0
	v_mov_b32_e32 v54, 0
	v_mov_b32_e32 v55, 0
	v_mov_b32_e32 v56, 0
	v_mov_b32_e32 v57, 0
	v_mov_b32_e32 v41, 1.0
	v_mov_b32_e32 v42, 1.0
	v_mov_b32_e32 v43, 1.0
	v_mov_b32_e32 v44, 1.0
	v_mov_b32_e32 v45, 1.0
	v_mov_b32_e32 v46, 1.0
	v_mov_b32_e32 v47, 1.0
	v_mov_b32_e32 v48, 1.0
	v_cmp_le_i32_e32 vcc, 0, v10
	s_and_saveexec_b64 s[24:25], vcc
	s_cbranch_execz .Lpw_skipw
	v_lshl_add_u64 v[28:29], v[26:27], 2, v[18:19]
	global_load_dword v2, v[28:29], off nt
	v_add_u32_e32 v26, s4, v26
	v_lshl_add_u64 v[28:29], v[26:27], 2, v[18:19]
	global_load_dword v9, v[28:29], off nt
	v_add_u32_e32 v26, s4, v26
	v_lshl_add_u64 v[28:29], v[26:27], 2, v[18:19]
	global_load_dword v4, v[28:29], off nt
	v_add_u32_e32 v26, s4, v26
	v_lshl_add_u64 v[28:29], v[26:27], 2, v[18:19]
	global_load_dword v3, v[28:29], off nt
	v_add_u32_e32 v26, s4, v26
	v_lshl_add_u64 v[28:29], v[26:27], 2, v[18:19]
	global_load_dword v6, v[28:29], off nt
	v_add_u32_e32 v26, s4, v26
	v_lshl_add_u64 v[28:29], v[26:27], 2, v[18:19]
	global_load_dword v5, v[28:29], off nt
	v_add_u32_e32 v26, s4, v26
	v_lshl_add_u64 v[28:29], v[26:27], 2, v[18:19]
	global_load_dword v8, v[28:29], off nt
	v_add_u32_e32 v26, s4, v26
	v_lshl_add_u64 v[28:29], v[26:27], 2, v[18:19]
	global_load_dword v7, v[28:29], off nt
.Lpw_skipw:
	s_or_b64 exec, exec, s[24:25]
	s_and_saveexec_b64 s[24:25], s[58:59]
	s_cbranch_execz .Lnp_skipb
	v_mul_lo_u32 v26, v16, s51
	v_add_co_u32_e32 v30, vcc, s60, v18
	v_addc_co_u32_e32 v31, vcc, 0, v19, vcc
	v_lshl_add_u64 v[28:29], v[26:27], 2, v[30:31]
	global_load_dword v50, v[28:29], off nt
	v_add_u32_e32 v26, s4, v26
	v_lshl_add_u64 v[28:29], v[26:27], 2, v[30:31]
	global_load_dword v51, v[28:29], off nt
	v_add_u32_e32 v26, s4, v26
	v_lshl_add_u64 v[28:29], v[26:27], 2, v[30:31]
	global_load_dword v52, v[28:29], off nt
	v_add_u32_e32 v26, s4, v26
	v_lshl_add_u64 v[28:29], v[26:27], 2, v[30:31]
	global_load_dword v53, v[28:29], off nt
	v_add_u32_e32 v26, s4, v26
	v_lshl_add_u64 v[28:29], v[26:27], 2, v[30:31]
	global_load_dword v54, v[28:29], off nt
	v_add_u32_e32 v26, s4, v26
	v_lshl_add_u64 v[28:29], v[26:27], 2, v[30:31]
	global_load_dword v55, v[28:29], off nt
	v_add_u32_e32 v26, s4, v26
	v_lshl_add_u64 v[28:29], v[26:27], 2, v[30:31]
	global_load_dword v56, v[28:29], off nt
	v_add_u32_e32 v26, s4, v26
	v_lshl_add_u64 v[28:29], v[26:27], 2, v[30:31]
	global_load_dword v57, v[28:29], off nt

; __device__ __forceinline__ unsigned pk2(float lo, float hi) { const pk_f32x2 v = {lo, hi}; const pk_bf16x2 b = __builtin_convertvector(v, pk_bf16x2); return __builtin_bit_cast(unsigned, b); }
; __device__ __forceinline__ void prologue_weights(KP kp, LAS float* tile, int wid0) {
;     ...
;         {
;             const int nl = tid >> 3, kc = tid & 7;
;             float o[8];
; #pragma unroll
;             for (int j = 0; j < 8; ++j) o[j] = tb[(kc * 8 + j) * 65 + nl];
;             u32x4 pk; pk.x = pk2(o[0], o[1]); pk.y = pk2(o[2], o[3]); pk.z = pk2(o[4], o[5]); pk.w = pk2(o[6], o[7]);
;             *(u32x4*)(w.dst + (size_t)(w.n0 + nl) * w.K + w.k0 + kc * 8) = pk;
;         }
;         if (!more) break;
;         w = wn; ti = tn; par ^= 1;
;     }
.Lpw_noks:
	s_cmp_eq_u32 s57, 0
	s_cbranch_scc1 .LBB0_157
	s_mov_b32 s57, 0
	s_branch .Lpw_latch
.LBB0_157:
	v_lshlrev_b32_e32 v10, 2, v13
	v_add3_u32 v10, s13, v10, v23
	ds_read2_b32 v[16:17], v10 offset1:65
	ds_read2_b32 v[18:19], v10 offset0:130 offset1:195
	v_add_u32_e32 v25, 0x4100, v10
	v_add_u32_e32 v10, 0x400, v10
	ds_read2_b32 v[26:27], v10 offset0:4 offset1:69
	ds_read2_b32 v[28:29], v10 offset0:134 offset1:199
	ds_read2_b32 v[30:31], v25 offset1:65
	ds_read2_b32 v[32:33], v25 offset0:130 offset1:195
	v_add_u32_e32 v25, 0x400, v25
	ds_read2_b32 v[34:35], v25 offset0:4 offset1:69
	ds_read2_b32 v[36:37], v25 offset0:134 offset1:199
	v_add_u32_e32 v10, s1, v13
	s_waitcnt lgkmcnt(7)
	v_cvt_pk_bf16_f32 v16, v16, v17
	s_waitcnt lgkmcnt(6)
	v_cvt_pk_bf16_f32 v17, v18, v19
	s_waitcnt lgkmcnt(5)
	v_cvt_pk_bf16_f32 v18, v26, v27
	v_mad_u64_u32 v[26:27], s[2:3], s0, v10, 0
	v_ashrrev_i32_e32 v15, 31, v10
	v_mov_b32_e32 v10, v27
	s_waitcnt lgkmcnt(4)
	v_cvt_pk_bf16_f32 v19, v28, v29
	v_mad_u64_u32 v[28:29], s[2:3], s0, v15, v[10:11]
	v_mov_b32_e32 v27, v28
	v_lshl_add_u64 v[26:27], v[26:27], 1, s[10:11]
	s_ashr_i32 s13, s12, 31
	v_lshl_add_u64 v[26:27], s[12:13], 1, v[26:27]
	v_mov_b32_e32 v15, v11
	v_lshl_add_u64 v[26:27], v[26:27], 0, v[14:15]
	s_lshl_b32 s2, s0, 7
	v_add_co_u32_e32 v38, vcc, s2, v26
	v_addc_co_u32_e32 v39, vcc, 0, v27, vcc
	s_waitcnt lgkmcnt(0)
	v_cvt_pk_bf16_f32 v30, v30, v31
	v_cvt_pk_bf16_f32 v31, v32, v33
	v_cvt_pk_bf16_f32 v32, v34, v35
	v_cvt_pk_bf16_f32 v33, v36, v37
	s_andn2_b64 vcc, exec, s[18:19]
	global_store_dwordx4 v[26:27], v[16:19], off
	global_store_dwordx4 v[38:39], v[30:33], off
	s_cbranch_vccnz .LBB0_82
.Lpw_latch:
	s_xor_b32 s48, s48, 1
	s_mov_b32 s1, s52
	s_mov_b32 s12, s53
	s_mov_b32 s0, s14
	s_mov_b64 s[10:11], s[20:21]
	s_mov_b32 s49, s56
	s_branch .LBB0_82
